# barrier before the prep phase: XCD leader skips the L2 write-back (the only cross-XCD data prep reads, Z, is stored write-through); sync and invalidates unchanged
# baseline (speedup 1.0000x reference)
.Lbar_global:
	s_mov_b64 s[4:5], exec
	v_readlane_b32 s6, v255, 40
	s_cmp_eq_u32 s6, 1
	s_cbranch_scc0 .Lgl_wb
	s_mul_hi_u32 s6, s17, 0x1999999a
	s_mul_i32 s6, s6, 10
	s_sub_i32 s6, s17, s6
	s_cmp_eq_u32 s6, 3
	s_cbranch_scc1 .Lgl_nowb
.Lgl_wb:
	buffer_wbl2 sc1
.Lgl_nowb:
	s_waitcnt lgkmcnt(0)
	s_waitcnt vmcnt(0)
	buffer_inv sc1
	v_mbcnt_lo_u32_b32 v3, s4, 0
	v_mbcnt_hi_u32_b32 v3, s5, v3
	v_cmp_eq_u32_e32 vcc, 0, v3
	s_and_saveexec_b64 s[6:7], vcc
	s_cbranch_execz .LBB0_44
	s_bcnt1_i32_b64 s4, s[4:5]
	v_mov_b32_e32 v4, s4
	v_readlane_b32 s4, v253, 10
	v_readlane_b32 s5, v253, 11
	s_nop 4
	global_atomic_add v4, v131, v4, s[4:5] sc0
